# chip-wide barrier: all waiters poll the cross-XCC arrival counter directly (two hops less per chip-wide seam)
# speedup vs baseline: 1.0093x; 1.0006x over previous
.LBB0_531:
	s_or_b64 exec, exec, s[8:9]
	v_cvt_f32_u32_e32 v4, v2
	s_waitcnt vmcnt(0)
	v_readfirstlane_b32 s8, v3
	v_sub_u32_e32 v3, 0, v2
	v_rcp_iflag_f32_e32 v4, v4
	v_add_u32_e32 v5, s8, v1
	v_mul_f32_e32 v4, 0x4f7ffffe, v4
	v_cvt_u32_f32_e32 v4, v4
	v_mul_lo_u32 v1, v3, v4
	v_mul_hi_u32 v1, v4, v1
	v_add_u32_e32 v1, v4, v1
	v_mul_hi_u32 v1, v5, v1
	v_mul_lo_u32 v3, v1, v2
	v_sub_u32_e32 v3, v5, v3
	v_add_u32_e32 v4, 1, v1
	v_cmp_ge_u32_e32 vcc, v3, v2
	s_nop 1
	v_cndmask_b32_e32 v1, v1, v4, vcc
	v_sub_u32_e32 v4, v3, v2
	v_cndmask_b32_e32 v3, v3, v4, vcc
	v_add_u32_e32 v4, 1, v1
	v_cmp_ge_u32_e32 vcc, v3, v2
	v_add_u32_e32 v3, 1, v5
	s_nop 0
	v_cndmask_b32_e32 v1, v1, v4, vcc
	v_mul_lo_u32 v4, v2, v1
	v_add_u32_e32 v2, v4, v2
	v_cmp_ne_u32_e32 vcc, v3, v2
	s_and_saveexec_b64 s[8:9], vcc
	s_xor_b64 s[8:9], exec, s[8:9]
	s_cbranch_execz .LBB0_545
	v_readlane_b32 s34, v234, 30
	v_readlane_b32 s35, v234, 31
	s_waitcnt lgkmcnt(0)
	v_add_u32_e32 v3, 1, v1
	v_mul_lo_u32 v3, v3, v0
	s_nop 3
	global_load_dword v0, v97, s[34:35] sc1
	s_waitcnt vmcnt(0)
	v_cmp_lt_u32_e32 vcc, v0, v3
	s_and_saveexec_b64 s[34:35], vcc
	s_cbranch_execz .LBB0_544
	s_mov_b32 s46, 1
	s_mov_b64 s[38:39], 0
	s_branch .LBB0_535

.LBB0_537:
	v_readlane_b32 s42, v234, 30
	v_readlane_b32 s43, v234, 31
	s_add_i32 s46, s46, 1
	s_mov_b64 s[72:73], -1
	s_nop 2
	global_load_dword v0, v97, s[42:43] sc1
	s_waitcnt vmcnt(0)
	v_cmp_ge_u32_e32 vcc, v0, v3
	s_orn2_b64 s[42:43], vcc, exec
	s_branch .LBB0_534

.LBB0_548:
	s_or_b64 exec, exec, s[34:35]
	s_waitcnt vmcnt(0)
	v_readfirstlane_b32 s8, v2
	v_cvt_f32_u32_e32 v2, v0
	v_sub_u32_e32 v3, 0, v0
	v_add_u32_e32 v1, s8, v1
	v_readlane_b32 s8, v234, 32
	v_rcp_iflag_f32_e32 v2, v2
	v_readlane_b32 s9, v234, 33
	s_mov_b64 s[34:35], -1
	v_mul_f32_e32 v2, 0x4f7ffffe, v2
	v_cvt_u32_f32_e32 v2, v2
	v_mul_lo_u32 v3, v3, v2
	v_mul_hi_u32 v3, v2, v3
	v_add_u32_e32 v2, v2, v3
	v_mul_hi_u32 v2, v1, v2
	v_mul_lo_u32 v3, v2, v0
	v_sub_u32_e32 v3, v1, v3
	v_cmp_ge_u32_e32 vcc, v3, v0
	v_add_u32_e32 v4, 1, v2
	v_add_u32_e32 v1, 1, v1
	v_cndmask_b32_e32 v2, v2, v4, vcc
	v_sub_u32_e32 v4, v3, v0
	v_cndmask_b32_e32 v3, v3, v4, vcc
	v_cmp_ge_u32_e32 vcc, v3, v0
	v_add_u32_e32 v3, 1, v2
	s_nop 0
	v_cndmask_b32_e32 v2, v2, v3, vcc
	v_mul_lo_u32 v3, v0, v2
	v_add_u32_e32 v0, v3, v0
	v_cmp_ne_u32_e32 vcc, v1, v0
	v_mov_b32_e32 v3, v0
	v_mov_b64_e32 v[0:1], s[8:9]
	s_and_saveexec_b64 s[8:9], vcc
	s_cbranch_execz .LBB0_560
	v_readlane_b32 s34, v234, 30
	v_readlane_b32 s35, v234, 31
	s_mov_b64 s[38:39], 0
	s_nop 3
	global_load_dword v0, v97, s[34:35] sc1
	s_waitcnt vmcnt(0)
	v_cmp_lt_u32_e32 vcc, v0, v3
	s_and_saveexec_b64 s[34:35], vcc
	s_cbranch_execz .LBB0_559
	s_mov_b32 s46, 1
	s_branch .LBB0_552
